# GLA prep score tile: 3-deep LDS fragment ring for the 8 chained MFMAs
# speedup vs baseline: 1.0037x; 1.0037x over previous
.LBB0_378:
	s_andn2_saveexec_b64 s[58:59], s[58:59]
	s_cbranch_execz .LBB0_380
	s_lshl_b64 s[62:63], s[64:65], 13
	v_readlane_b32 s64, v238, 8
	s_add_u32 s62, s74, s62
	v_readlane_b32 s65, v238, 9
	s_addc_u32 s63, s75, s63
	ds_read_b128 v[146:149], v195
	ds_read_b128 v[150:153], v196 offset:17408
	ds_read_b128 v[240:243], v195 offset:32
	ds_read_b128 v[244:247], v196 offset:17440
	ds_read_b128 v[248:251], v195 offset:64
	ds_read_b128 v[252:255], v196 offset:17472
	s_waitcnt lgkmcnt(4)
	v_mfma_f32_32x32x16_bf16 v[0:15], v[146:149], v[150:153], 0
	ds_read_b128 v[146:149], v195 offset:96
	ds_read_b128 v[150:153], v196 offset:17504
	s_waitcnt lgkmcnt(4)
	v_mfma_f32_32x32x16_bf16 v[0:15], v[240:243], v[244:247], v[0:15]
	ds_read_b128 v[240:243], v195 offset:128
	ds_read_b128 v[244:247], v196 offset:17536
	s_waitcnt lgkmcnt(4)
	v_mfma_f32_32x32x16_bf16 v[0:15], v[248:251], v[252:255], v[0:15]
	ds_read_b128 v[248:251], v195 offset:160
	ds_read_b128 v[252:255], v196 offset:17568
	s_waitcnt lgkmcnt(4)
	v_mfma_f32_32x32x16_bf16 v[0:15], v[146:149], v[150:153], v[0:15]
	ds_read_b128 v[146:149], v195 offset:192
	ds_read_b128 v[150:153], v196 offset:17600
	s_waitcnt lgkmcnt(4)
	v_mfma_f32_32x32x16_bf16 v[0:15], v[240:243], v[244:247], v[0:15]
	ds_read_b128 v[240:243], v195 offset:224
	ds_read_b128 v[244:247], v196 offset:17632
	s_waitcnt lgkmcnt(4)
	v_mfma_f32_32x32x16_bf16 v[0:15], v[248:251], v[252:255], v[0:15]
	s_waitcnt lgkmcnt(2)
	v_mfma_f32_32x32x16_bf16 v[0:15], v[146:149], v[150:153], v[0:15]
	s_waitcnt lgkmcnt(0)
	v_mfma_f32_32x32x16_bf16 v[0:15], v[240:243], v[244:247], v[0:15]
	v_lshlrev_b32_e32 v146, 1, v62
	s_nop 10
	v_cvt_pk_bf16_f32 v0, v0, s0
	v_cndmask_b32_e64 v0, v0, 0, s[64:65]
	v_readlane_b32 s64, v238, 14
	global_store_short v146, v0, s[62:63]
	v_cvt_pk_bf16_f32 v0, v1, s0
	v_readlane_b32 s65, v238, 15
	v_lshlrev_b32_e32 v1, 1, v64
	s_nop 0
	v_cndmask_b32_e64 v0, v0, 0, s[64:65]
	global_store_short v1, v0, s[62:63]
	v_cvt_pk_bf16_f32 v0, v2, s0
	v_cndmask_b32_e64 v0, v0, 0, s[26:27]
	v_lshlrev_b32_e32 v1, 1, v66
	global_store_short v1, v0, s[62:63]
	v_cvt_pk_bf16_f32 v0, v3, s0
	v_cndmask_b32_e64 v0, v0, 0, s[28:29]
	v_lshlrev_b32_e32 v1, 1, v72
	global_store_short v1, v0, s[62:63]
	v_cvt_pk_bf16_f32 v0, v4, s0
	v_cndmask_b32_e64 v0, v0, 0, s[30:31]
	v_lshlrev_b32_e32 v1, 1, v74
	global_store_short v1, v0, s[62:63]
	v_cvt_pk_bf16_f32 v0, v5, s0
	v_cndmask_b32_e64 v0, v0, 0, s[34:35]
	v_lshlrev_b32_e32 v1, 1, v76
	global_store_short v1, v0, s[62:63]
	v_cvt_pk_bf16_f32 v0, v6, s0
	v_cndmask_b32_e64 v0, v0, 0, s[36:37]
	v_lshlrev_b32_e32 v1, 1, v78
	global_store_short v1, v0, s[62:63]
	v_cvt_pk_bf16_f32 v0, v7, s0
	v_cndmask_b32_e64 v0, v0, 0, s[38:39]
	v_lshlrev_b32_e32 v1, 1, v80
	global_store_short v1, v0, s[62:63]
	v_cvt_pk_bf16_f32 v0, v8, s0
	v_cndmask_b32_e64 v0, v0, 0, s[40:41]
	v_lshlrev_b32_e32 v1, 1, v82
	global_store_short v1, v0, s[62:63]
	v_cvt_pk_bf16_f32 v0, v9, s0
	v_cndmask_b32_e64 v0, v0, 0, s[42:43]
	v_lshlrev_b32_e32 v1, 1, v84
	global_store_short v1, v0, s[62:63]
	v_cvt_pk_bf16_f32 v0, v10, s0
	v_cndmask_b32_e64 v0, v0, 0, s[44:45]
	v_lshlrev_b32_e32 v1, 1, v86
	global_store_short v1, v0, s[62:63]
	v_cvt_pk_bf16_f32 v0, v11, s0
	v_cndmask_b32_e64 v0, v0, 0, s[46:47]
	v_lshlrev_b32_e32 v1, 1, v88
	global_store_short v1, v0, s[62:63]
	v_cvt_pk_bf16_f32 v0, v12, s0
	v_cndmask_b32_e64 v0, v0, 0, s[48:49]
	v_lshlrev_b32_e32 v1, 1, v90
	global_store_short v1, v0, s[62:63]
	v_cvt_pk_bf16_f32 v0, v13, s0
	v_cndmask_b32_e64 v0, v0, 0, s[50:51]
	v_lshlrev_b32_e32 v1, 1, v92
	global_store_short v1, v0, s[62:63]
	v_cvt_pk_bf16_f32 v0, v14, s0
	v_cndmask_b32_e64 v0, v0, 0, s[52:53]
	v_lshlrev_b32_e32 v1, 1, v96
	global_store_short v1, v0, s[62:63]
	v_cvt_pk_bf16_f32 v0, v15, s0
	v_cndmask_b32_e64 v0, v0, 0, s[54:55]
	v_lshlrev_b32_e32 v1, 1, v100
	global_store_short v1, v0, s[62:63]
